# de-serialized dependent load chains: adaLN partial-sum loop (64 loads pipelined 32 deep), adaLN reduce (16 loads in flight), norm row loop (8 loads per iteration up front)
# speedup vs baseline: 1.0333x; 1.0333x over previous
.LBB0_31:
	v_lshl_add_u64 v[6:7], s[2:3], 0, v[4:5]
	global_load_dword v80, v[6:7], off
	v_add_co_u32_e32 v8, vcc, 0x30000, v6
	s_nop 1
	v_addc_co_u32_e32 v9, vcc, 0, v7, vcc
	global_load_dword v81, v[8:9], off
	v_add_co_u32_e32 v8, vcc, 0x60000, v6
	s_nop 1
	v_addc_co_u32_e32 v9, vcc, 0, v7, vcc
	global_load_dword v82, v[8:9], off
	v_add_co_u32_e32 v8, vcc, 0x90000, v6
	s_nop 1
	v_addc_co_u32_e32 v9, vcc, 0, v7, vcc
	global_load_dword v83, v[8:9], off
	v_add_co_u32_e32 v8, vcc, 0xc0000, v6
	s_nop 1
	v_addc_co_u32_e32 v9, vcc, 0, v7, vcc
	global_load_dword v84, v[8:9], off
	v_add_co_u32_e32 v8, vcc, 0xf0000, v6
	s_nop 1
	v_addc_co_u32_e32 v9, vcc, 0, v7, vcc
	global_load_dword v85, v[8:9], off
	v_add_co_u32_e32 v8, vcc, 0x120000, v6
	s_nop 1
	v_addc_co_u32_e32 v9, vcc, 0, v7, vcc
	global_load_dword v86, v[8:9], off
	v_add_co_u32_e32 v8, vcc, 0x150000, v6
	s_nop 1
	v_addc_co_u32_e32 v9, vcc, 0, v7, vcc
	global_load_dword v87, v[8:9], off
	v_add_co_u32_e32 v8, vcc, 0x180000, v6
	s_nop 1
	v_addc_co_u32_e32 v9, vcc, 0, v7, vcc
	global_load_dword v88, v[8:9], off
	v_add_co_u32_e32 v8, vcc, 0x1b0000, v6
	s_nop 1
	v_addc_co_u32_e32 v9, vcc, 0, v7, vcc
	global_load_dword v89, v[8:9], off
	v_add_co_u32_e32 v8, vcc, 0x1e0000, v6
	s_nop 1
	v_addc_co_u32_e32 v9, vcc, 0, v7, vcc
	global_load_dword v90, v[8:9], off
	v_add_co_u32_e32 v8, vcc, 0x210000, v6
	s_nop 1
	v_addc_co_u32_e32 v9, vcc, 0, v7, vcc
	global_load_dword v91, v[8:9], off
	v_add_co_u32_e32 v8, vcc, 0x240000, v6
	s_nop 1
	v_addc_co_u32_e32 v9, vcc, 0, v7, vcc
	global_load_dword v92, v[8:9], off
	v_add_co_u32_e32 v8, vcc, 0x270000, v6
	s_nop 1
	v_addc_co_u32_e32 v9, vcc, 0, v7, vcc
	global_load_dword v93, v[8:9], off
	v_add_co_u32_e32 v8, vcc, 0x2a0000, v6
	s_nop 1
	v_addc_co_u32_e32 v9, vcc, 0, v7, vcc
	global_load_dword v94, v[8:9], off
	v_add_co_u32_e32 v8, vcc, 0x2d0000, v6
	v_add_u32_e32 v2, s84, v2
	s_mov_b32 s10, 0xbfff
	v_addc_co_u32_e32 v9, vcc, 0, v7, vcc
	global_load_dword v95, v[8:9], off
	v_lshl_add_u64 v[6:7], s[4:5], 0, v[4:5]
	s_add_u32 s4, s4, s92
	s_addc_u32 s5, s5, s93
	s_add_u32 s2, s2, s92
	s_addc_u32 s3, s3, s93
	v_cmp_lt_i32_e32 vcc, s10, v2
	s_or_b64 s[8:9], vcc, s[8:9]
	s_waitcnt vmcnt(15)
	v_add_f32_e32 v0, 0, v80
	s_waitcnt vmcnt(14)
	v_add_f32_e32 v0, v0, v81
	s_waitcnt vmcnt(13)
	v_add_f32_e32 v0, v0, v82
	s_waitcnt vmcnt(12)
	v_add_f32_e32 v0, v0, v83
	s_waitcnt vmcnt(11)
	v_add_f32_e32 v0, v0, v84
	s_waitcnt vmcnt(10)
	v_add_f32_e32 v0, v0, v85
	s_waitcnt vmcnt(9)
	v_add_f32_e32 v0, v0, v86
	s_waitcnt vmcnt(8)
	v_add_f32_e32 v0, v0, v87
	s_waitcnt vmcnt(7)
	v_add_f32_e32 v0, v0, v88
	s_waitcnt vmcnt(6)
	v_add_f32_e32 v0, v0, v89
	s_waitcnt vmcnt(5)
	v_add_f32_e32 v0, v0, v90
	s_waitcnt vmcnt(4)
	v_add_f32_e32 v0, v0, v91
	s_waitcnt vmcnt(3)
	v_add_f32_e32 v0, v0, v92
	s_waitcnt vmcnt(2)
	v_add_f32_e32 v0, v0, v93
	s_waitcnt vmcnt(1)
	v_add_f32_e32 v0, v0, v94
	s_waitcnt vmcnt(0)
	v_add_f32_e32 v0, v0, v95
	global_store_dword v[6:7], v0, off
	s_andn2_b64 exec, exec, s[8:9]
	s_cbranch_execnz .LBB0_31

.LBB0_204:
	v_lshl_add_u64 v[64:65], v[44:45], 0, s[8:9]
	global_load_dwordx4 v[70:73], v[64:65], off nt
	global_load_dwordx4 v[74:77], v[64:65], off offset:1024 nt
	global_load_dwordx4 v[78:81], v[64:65], off offset:2048 nt
	global_load_dwordx4 v[82:85], v[64:65], off offset:3072 nt
	v_ashrrev_i32_e32 v63, 31, v62
	v_lshlrev_b64 v[104:105], 12, v[62:63]
	v_lshl_add_u64 v[104:105], v[18:19], 0, v[104:105]
	global_load_dwordx4 v[112:115], v[104:105], off nt
	global_load_dwordx4 v[116:119], v[104:105], off offset:1024 nt
	global_load_dwordx4 v[120:123], v[104:105], off offset:2048 nt
	global_load_dwordx4 v[124:127], v[104:105], off offset:3072 nt
	s_add_u32 s8, s8, 0x2000
	s_addc_u32 s9, s9, 0
	s_cmpk_eq_u32 s8, 0x8000
	s_waitcnt vmcnt(7)
	v_mov_b32_e32 v108, v71
	s_waitcnt vmcnt(6)
	v_mov_b32_e32 v109, v75
	v_mov_b32_e32 v106, v70
	v_mov_b32_e32 v107, v74
	v_pk_mul_f32 v[108:109], v[108:109], v[108:109]
	s_nop 0
	v_pk_fma_f32 v[106:107], v[106:107], v[106:107], v[108:109]
	v_mov_b32_e32 v108, v72
	v_mov_b32_e32 v109, v76
	v_pk_fma_f32 v[106:107], v[108:109], v[108:109], v[106:107]
	v_mov_b32_e32 v108, v73
	v_mov_b32_e32 v109, v77
	v_pk_fma_f32 v[86:87], v[108:109], v[108:109], v[106:107]
	v_add_f32_e32 v33, v86, v87
	v_and_b32_e32 v87, 0x3ffffff, v43
	s_waitcnt vmcnt(5)
	v_mov_b32_e32 v88, v79
	s_waitcnt vmcnt(4)
	v_mov_b32_e32 v89, v83
	v_mov_b32_e32 v64, v78
	v_mov_b32_e32 v65, v82
	v_pk_mul_f32 v[88:89], v[88:89], v[88:89]
	s_nop 0
	v_pk_fma_f32 v[64:65], v[64:65], v[64:65], v[88:89]
	v_mov_b32_e32 v88, v80
	v_mov_b32_e32 v89, v84
	v_pk_fma_f32 v[64:65], v[88:89], v[88:89], v[64:65]
	v_mov_b32_e32 v88, v81
	v_mov_b32_e32 v89, v85
	v_pk_fma_f32 v[64:65], v[88:89], v[88:89], v[64:65]
	s_nop 0
	v_add_f32_e32 v33, v33, v64
	v_add_f32_e32 v33, v33, v65
	ds_bpermute_b32 v37, v27, v33
	s_waitcnt lgkmcnt(0)
	v_add_f32_e32 v33, v33, v37
	ds_bpermute_b32 v37, v29, v33
	s_waitcnt lgkmcnt(0)
	v_add_f32_e32 v33, v33, v37
	ds_bpermute_b32 v37, v31, v33
	s_waitcnt lgkmcnt(0)
	v_add_f32_e32 v33, v33, v37
	ds_bpermute_b32 v37, v66, v33
	s_waitcnt lgkmcnt(0)
	v_add_f32_e32 v33, v33, v37
	ds_bpermute_b32 v37, v67, v33
	s_waitcnt lgkmcnt(0)
	v_add_f32_e32 v33, v33, v37
	ds_bpermute_b32 v37, v68, v33
	s_waitcnt lgkmcnt(0)
	v_add_f32_e32 v33, v33, v37
	v_fmamk_f32 v33, v33, 0x3a800000, v202
	v_cmp_gt_f32_e32 vcc, s74, v33
	v_mul_f32_e32 v37, 0x4b800000, v33
	s_nop 0
	v_cndmask_b32_e32 v33, v33, v37, vcc
	v_rsq_f32_e32 v33, v33
	s_nop 0
	v_mul_f32_e32 v37, 0x45800000, v33
	v_cndmask_b32_e32 v64, v33, v37, vcc
	v_and_b32_e32 v33, 0xffffffe0, v42
	v_pk_mul_f32 v[70:71], v[70:71], v[64:65] op_sel_hi:[1,0]
	v_pk_mul_f32 v[72:73], v[72:73], v[64:65] op_sel_hi:[1,0]
	v_pk_fma_f32 v[70:71], v[48:49], v[70:71], v[2:3]
	v_pk_fma_f32 v[72:73], v[46:47], v[72:73], v[4:5]
	v_or_b32_e32 v86, v33, v24
	v_cvt_pk_bf16_f32 v70, v70, v71
	v_cvt_pk_bf16_f32 v71, v72, v73
	v_lshlrev_b64 v[72:73], 7, v[86:87]
	v_lshl_add_u64 v[72:73], v[20:21], 0, v[72:73]
	global_store_dwordx2 v[72:73], v[70:71], off
	v_pk_mul_f32 v[70:71], v[74:75], v[64:65] op_sel_hi:[1,0]
	v_pk_mul_f32 v[72:73], v[76:77], v[64:65] op_sel_hi:[1,0]
	v_pk_fma_f32 v[70:71], v[52:53], v[70:71], v[6:7]
	v_pk_fma_f32 v[72:73], v[50:51], v[72:73], v[8:9]
	v_or_b32_e32 v86, v33, v26
	v_cvt_pk_bf16_f32 v70, v70, v71
	v_cvt_pk_bf16_f32 v71, v72, v73
	v_lshlrev_b64 v[72:73], 7, v[86:87]
	v_lshl_add_u64 v[72:73], v[20:21], 0, v[72:73]
	global_store_dwordx2 v[72:73], v[70:71], off
	v_pk_mul_f32 v[70:71], v[78:79], v[64:65] op_sel_hi:[1,0]
	v_pk_mul_f32 v[72:73], v[80:81], v[64:65] op_sel_hi:[1,0]
	v_pk_fma_f32 v[70:71], v[56:57], v[70:71], v[10:11]
	v_pk_fma_f32 v[72:73], v[54:55], v[72:73], v[12:13]
	v_or_b32_e32 v86, v33, v28
	v_cvt_pk_bf16_f32 v70, v70, v71
	v_cvt_pk_bf16_f32 v71, v72, v73
	v_lshlrev_b64 v[72:73], 7, v[86:87]
	v_lshl_add_u64 v[72:73], v[20:21], 0, v[72:73]
	global_store_dwordx2 v[72:73], v[70:71], off
	v_pk_mul_f32 v[70:71], v[82:83], v[64:65] op_sel_hi:[1,0]
	v_pk_mul_f32 v[64:65], v[84:85], v[64:65] op_sel_hi:[1,0]
	v_pk_fma_f32 v[70:71], v[60:61], v[70:71], v[14:15]
	v_pk_fma_f32 v[64:65], v[58:59], v[64:65], v[16:17]
	v_or_b32_e32 v86, v33, v30
	v_cvt_pk_bf16_f32 v70, v70, v71
	v_cvt_pk_bf16_f32 v71, v64, v65
	v_lshlrev_b64 v[64:65], 7, v[86:87]
	v_lshl_add_u64 v[64:65], v[20:21], 0, v[64:65]
	global_store_dwordx2 v[64:65], v[70:71], off
	v_lshl_add_u64 v[42:43], v[42:43], 0, 32
	s_waitcnt vmcnt(7)
	v_mov_b32_e32 v108, v113
	s_waitcnt vmcnt(6)
	v_mov_b32_e32 v109, v117
	v_mov_b32_e32 v106, v112
	v_mov_b32_e32 v107, v116
	v_pk_mul_f32 v[108:109], v[108:109], v[108:109]
	s_nop 0
	v_pk_fma_f32 v[106:107], v[106:107], v[106:107], v[108:109]
	v_mov_b32_e32 v108, v114
	v_mov_b32_e32 v109, v118
	v_pk_fma_f32 v[106:107], v[108:109], v[108:109], v[106:107]
	v_mov_b32_e32 v108, v115
	v_mov_b32_e32 v109, v119
	v_pk_fma_f32 v[86:87], v[108:109], v[108:109], v[106:107]
	v_add_f32_e32 v33, v86, v87
	v_lshlrev_b64 v[86:87], 4, v[62:63]
	v_and_b32_e32 v87, 0x3ffffff, v87
	v_add_u32_e32 v62, 2, v62
	s_waitcnt vmcnt(5)
	v_mov_b32_e32 v88, v121
	s_waitcnt vmcnt(4)
	v_mov_b32_e32 v89, v125
	v_mov_b32_e32 v64, v120
	v_mov_b32_e32 v65, v124
	v_pk_mul_f32 v[88:89], v[88:89], v[88:89]
	s_nop 0
	v_pk_fma_f32 v[64:65], v[64:65], v[64:65], v[88:89]
	v_mov_b32_e32 v88, v122
	v_mov_b32_e32 v89, v126
	v_pk_fma_f32 v[64:65], v[88:89], v[88:89], v[64:65]
	v_mov_b32_e32 v88, v123
	v_mov_b32_e32 v89, v127
	v_pk_fma_f32 v[64:65], v[88:89], v[88:89], v[64:65]
	s_nop 0
	v_add_f32_e32 v33, v33, v64
	v_add_f32_e32 v33, v33, v65
	ds_bpermute_b32 v37, v27, v33
	s_waitcnt lgkmcnt(0)
	v_add_f32_e32 v33, v33, v37
	ds_bpermute_b32 v37, v29, v33
	s_waitcnt lgkmcnt(0)
	v_add_f32_e32 v33, v33, v37
	ds_bpermute_b32 v37, v31, v33
	s_waitcnt lgkmcnt(0)
	v_add_f32_e32 v33, v33, v37
	ds_bpermute_b32 v37, v66, v33
	s_waitcnt lgkmcnt(0)
	v_add_f32_e32 v33, v33, v37
	ds_bpermute_b32 v37, v67, v33
	s_waitcnt lgkmcnt(0)
	v_add_f32_e32 v33, v33, v37
	ds_bpermute_b32 v37, v68, v33
	s_waitcnt lgkmcnt(0)
	v_add_f32_e32 v33, v33, v37
	v_fmamk_f32 v33, v33, 0x3a800000, v202
	v_cmp_gt_f32_e32 vcc, s74, v33
	v_mul_f32_e32 v37, 0x4b800000, v33
	s_nop 0
	v_cndmask_b32_e32 v33, v33, v37, vcc
	v_rsq_f32_e32 v33, v33
	s_nop 0
	v_mul_f32_e32 v37, 0x45800000, v33
	v_cndmask_b32_e32 v64, v33, v37, vcc
	v_and_b32_e32 v33, 0xffffffe0, v86
	v_pk_mul_f32 v[112:113], v[112:113], v[64:65] op_sel_hi:[1,0]
	v_pk_mul_f32 v[114:115], v[114:115], v[64:65] op_sel_hi:[1,0]
	v_pk_fma_f32 v[112:113], v[48:49], v[112:113], v[2:3]
	v_pk_fma_f32 v[114:115], v[46:47], v[114:115], v[4:5]
	v_or_b32_e32 v86, v33, v24
	v_cvt_pk_bf16_f32 v112, v112, v113
	v_cvt_pk_bf16_f32 v113, v114, v115
	v_lshlrev_b64 v[114:115], 7, v[86:87]
	v_lshl_add_u64 v[114:115], v[20:21], 0, v[114:115]
	global_store_dwordx2 v[114:115], v[112:113], off offset:64
	v_pk_mul_f32 v[112:113], v[116:117], v[64:65] op_sel_hi:[1,0]
	v_pk_mul_f32 v[114:115], v[118:119], v[64:65] op_sel_hi:[1,0]
	v_pk_fma_f32 v[112:113], v[52:53], v[112:113], v[6:7]
	v_pk_fma_f32 v[114:115], v[50:51], v[114:115], v[8:9]
	v_or_b32_e32 v86, v33, v26
	v_cvt_pk_bf16_f32 v112, v112, v113
	v_cvt_pk_bf16_f32 v113, v114, v115
	v_lshlrev_b64 v[114:115], 7, v[86:87]
	v_lshl_add_u64 v[114:115], v[20:21], 0, v[114:115]
	global_store_dwordx2 v[114:115], v[112:113], off offset:64
	v_pk_mul_f32 v[112:113], v[120:121], v[64:65] op_sel_hi:[1,0]
	v_pk_mul_f32 v[114:115], v[122:123], v[64:65] op_sel_hi:[1,0]
	v_pk_fma_f32 v[112:113], v[56:57], v[112:113], v[10:11]
	v_pk_fma_f32 v[114:115], v[54:55], v[114:115], v[12:13]
	v_or_b32_e32 v86, v33, v28
	v_cvt_pk_bf16_f32 v112, v112, v113
	v_cvt_pk_bf16_f32 v113, v114, v115
	v_lshlrev_b64 v[114:115], 7, v[86:87]
	v_lshl_add_u64 v[114:115], v[20:21], 0, v[114:115]
	global_store_dwordx2 v[114:115], v[112:113], off offset:64
	v_pk_mul_f32 v[112:113], v[124:125], v[64:65] op_sel_hi:[1,0]
	v_pk_mul_f32 v[64:65], v[126:127], v[64:65] op_sel_hi:[1,0]
	v_pk_fma_f32 v[112:113], v[60:61], v[112:113], v[14:15]
	v_pk_fma_f32 v[64:65], v[58:59], v[64:65], v[16:17]
	v_or_b32_e32 v86, v33, v30
	v_cvt_pk_bf16_f32 v112, v112, v113
	v_cvt_pk_bf16_f32 v113, v64, v65
	v_lshlrev_b64 v[64:65], 7, v[86:87]
	v_lshl_add_u64 v[64:65], v[20:21], 0, v[64:65]
	global_store_dwordx2 v[64:65], v[112:113], off offset:64
	s_cbranch_scc0 .LBB0_204
	v_add_u32_e32 v25, s86, v25
	s_movk_i32 s8, 0x7ff
	v_cmp_lt_i32_e32 vcc, s8, v25
	v_add_u32_e32 v69, s85, v69
	s_or_b64 s[6:7], vcc, s[6:7]
	v_add_u32_e32 v32, s85, v32
	s_andn2_b64 exec, exec, s[6:7]
	s_cbranch_execnz .LBB0_203
	s_branch .LBB0_198

.LBB0_335:
	s_and_b64 vcc, exec, s[0:1]
	s_cbranch_vccz .LBB0_341
	s_add_i32 s0, s68, 0xf680
	s_and_b32 s1, s0, 0xffff
	s_mul_i32 s1, s1, 0xaaab
	s_lshr_b32 s1, s1, 23
	s_mul_i32 s4, s1, 0xc0
	s_sub_i32 s0, s0, s4
	s_and_b32 s8, s0, 0xffff
	s_and_b32 s0, s0, 15
	s_lshl_b32 s9, s0, 6
	v_or_b32_e32 v2, s9, v40
	v_ashrrev_i32_e32 v3, 31, v2
	v_lshl_add_u64 v[2:3], v[2:3], 2, s[2:3]
	global_load_dword v0, v[2:3], off
	v_mov_b32_e32 v32, 0
	s_mov_b64 s[92:93], 0
	v_mov_b32_e32 v33, v32
	v_mov_b32_e32 v34, v32
	v_mov_b32_e32 v35, v32
	s_waitcnt vmcnt(0)
	v_mul_f32_e32 v2, 0xbfb8aa3b, v0
	v_fma_f32 v3, v0, s36, -v2
	v_rndne_f32_e32 v4, v2
	v_fmac_f32_e32 v3, 0xb2a5705f, v0
	v_sub_f32_e32 v2, v2, v4
	v_add_f32_e32 v2, v2, v3
	v_exp_f32_e32 v2, v2
	v_cvt_i32_f32_e32 v3, v4
	v_cmp_nlt_f32_e32 vcc, s81, v0
	v_ldexp_f32 v2, v2, v3
	s_nop 0
	v_cndmask_b32_e32 v2, 0, v2, vcc
	v_cmp_ngt_f32_e32 vcc, s33, v0
	s_nop 1
	v_cndmask_b32_e32 v2, v216, v2, vcc
	v_add_f32_e32 v2, 1.0, v2
	v_div_scale_f32 v3, s[4:5], v2, v2, v0
	v_rcp_f32_e32 v4, v3
	s_lshl_b32 s4, s8, 4
	s_and_b32 s4, s4, 0xf00
	v_fma_f32 v5, -v3, v4, 1.0
	v_fmac_f32_e32 v4, v5, v4
	v_div_scale_f32 v5, vcc, v0, v2, v0
	v_mul_f32_e32 v8, v5, v4
	v_fma_f32 v28, -v3, v8, v5
	v_fmac_f32_e32 v8, v28, v4
	v_add_u32_e32 v28, s4, v38
	s_lshl_b32 s4, s1, 10
	s_or_b32 s4, s4, s9
	s_mul_hi_u32 s5, s4, 0x3000
	s_mulk_i32 s4, 0x3000
	v_fma_f32 v3, -v3, v8, v5
	s_add_u32 s4, s6, s4
	v_div_fmas_f32 v3, v3, v4, v8
	s_addc_u32 s5, s7, s5
	v_ashrrev_i32_e32 v29, 31, v28
	v_div_fixup_f32 v0, v3, v2, v0
	v_lshl_add_u64 v[30:31], v[28:29], 2, s[4:5]
	s_mov_b32 s4, 0
	ds_write_b32 v41, v0
	s_waitcnt lgkmcnt(0)
	s_barrier
	s_mov_b64 s[92:93], 0x3000
	v_mov_b32_e32 v8, 0
	v_mov_b64_e32 v[36:37], v[30:31]
	global_load_dword v80, v[36:37], off nt
	v_lshl_add_u64 v[36:37], v[36:37], 0, s[92:93]
	global_load_dword v81, v[36:37], off nt
	v_lshl_add_u64 v[36:37], v[36:37], 0, s[92:93]
	global_load_dword v82, v[36:37], off nt
	v_lshl_add_u64 v[36:37], v[36:37], 0, s[92:93]
	global_load_dword v83, v[36:37], off nt
	v_lshl_add_u64 v[36:37], v[36:37], 0, s[92:93]
	global_load_dword v84, v[36:37], off nt
	v_lshl_add_u64 v[36:37], v[36:37], 0, s[92:93]
	global_load_dword v85, v[36:37], off nt
	v_lshl_add_u64 v[36:37], v[36:37], 0, s[92:93]
	global_load_dword v86, v[36:37], off nt
	v_lshl_add_u64 v[36:37], v[36:37], 0, s[92:93]
	global_load_dword v87, v[36:37], off nt
	v_lshl_add_u64 v[36:37], v[36:37], 0, s[92:93]
	global_load_dword v88, v[36:37], off nt
	v_lshl_add_u64 v[36:37], v[36:37], 0, s[92:93]
	global_load_dword v89, v[36:37], off nt
	v_lshl_add_u64 v[36:37], v[36:37], 0, s[92:93]
	global_load_dword v90, v[36:37], off nt
	v_lshl_add_u64 v[36:37], v[36:37], 0, s[92:93]
	global_load_dword v91, v[36:37], off nt
	v_lshl_add_u64 v[36:37], v[36:37], 0, s[92:93]
	global_load_dword v92, v[36:37], off nt
	v_lshl_add_u64 v[36:37], v[36:37], 0, s[92:93]
	global_load_dword v93, v[36:37], off nt
	v_lshl_add_u64 v[36:37], v[36:37], 0, s[92:93]
	global_load_dword v94, v[36:37], off nt
	v_lshl_add_u64 v[36:37], v[36:37], 0, s[92:93]
	global_load_dword v95, v[36:37], off nt
	v_lshl_add_u64 v[36:37], v[36:37], 0, s[92:93]
	global_load_dword v96, v[36:37], off nt
	v_lshl_add_u64 v[36:37], v[36:37], 0, s[92:93]
	global_load_dword v97, v[36:37], off nt
	v_lshl_add_u64 v[36:37], v[36:37], 0, s[92:93]
	global_load_dword v98, v[36:37], off nt
	v_lshl_add_u64 v[36:37], v[36:37], 0, s[92:93]
	global_load_dword v99, v[36:37], off nt
	v_lshl_add_u64 v[36:37], v[36:37], 0, s[92:93]
	global_load_dword v100, v[36:37], off nt
	v_lshl_add_u64 v[36:37], v[36:37], 0, s[92:93]
	global_load_dword v101, v[36:37], off nt
	v_lshl_add_u64 v[36:37], v[36:37], 0, s[92:93]
	global_load_dword v102, v[36:37], off nt
	v_lshl_add_u64 v[36:37], v[36:37], 0, s[92:93]
	global_load_dword v103, v[36:37], off nt
	v_lshl_add_u64 v[36:37], v[36:37], 0, s[92:93]
	global_load_dword v104, v[36:37], off nt
	v_lshl_add_u64 v[36:37], v[36:37], 0, s[92:93]
	global_load_dword v105, v[36:37], off nt
	v_lshl_add_u64 v[36:37], v[36:37], 0, s[92:93]
	global_load_dword v106, v[36:37], off nt
	v_lshl_add_u64 v[36:37], v[36:37], 0, s[92:93]
	global_load_dword v107, v[36:37], off nt
	v_lshl_add_u64 v[36:37], v[36:37], 0, s[92:93]
	global_load_dword v108, v[36:37], off nt
	v_lshl_add_u64 v[36:37], v[36:37], 0, s[92:93]
	global_load_dword v109, v[36:37], off nt
	v_lshl_add_u64 v[36:37], v[36:37], 0, s[92:93]
	global_load_dword v110, v[36:37], off nt
	v_lshl_add_u64 v[36:37], v[36:37], 0, s[92:93]
	global_load_dword v111, v[36:37], off nt
	v_lshl_add_u64 v[36:37], v[36:37], 0, s[92:93]
	ds_read_b128 v[48:51], v8 offset:0
	ds_read_b128 v[52:55], v8 offset:256
	ds_read_b128 v[56:59], v8 offset:512
	ds_read_b128 v[60:63], v8 offset:768
	ds_read_b128 v[64:67], v8 offset:16
	ds_read_b128 v[68:71], v8 offset:272
	ds_read_b128 v[72:75], v8 offset:528
	ds_read_b128 v[76:79], v8 offset:784
	s_waitcnt lgkmcnt(4)
	s_waitcnt vmcnt(28)
	v_fmac_f32_e32 v35, v48, v80
	v_fmac_f32_e32 v34, v52, v80
	v_fmac_f32_e32 v33, v56, v80
	v_fmac_f32_e32 v32, v60, v80
	v_fmac_f32_e32 v35, v49, v81
	v_fmac_f32_e32 v34, v53, v81
	v_fmac_f32_e32 v33, v57, v81
	v_fmac_f32_e32 v32, v61, v81
	v_fmac_f32_e32 v35, v50, v82
	v_fmac_f32_e32 v34, v54, v82
	v_fmac_f32_e32 v33, v58, v82
	v_fmac_f32_e32 v32, v62, v82
	v_fmac_f32_e32 v35, v51, v83
	v_fmac_f32_e32 v34, v55, v83
	v_fmac_f32_e32 v33, v59, v83
	v_fmac_f32_e32 v32, v63, v83
	global_load_dword v112, v[36:37], off nt
	v_lshl_add_u64 v[36:37], v[36:37], 0, s[92:93]
	global_load_dword v113, v[36:37], off nt
	v_lshl_add_u64 v[36:37], v[36:37], 0, s[92:93]
	global_load_dword v114, v[36:37], off nt
	v_lshl_add_u64 v[36:37], v[36:37], 0, s[92:93]
	global_load_dword v115, v[36:37], off nt
	v_lshl_add_u64 v[36:37], v[36:37], 0, s[92:93]
	ds_read_b128 v[48:51], v8 offset:32
	ds_read_b128 v[52:55], v8 offset:288
	ds_read_b128 v[56:59], v8 offset:544
	ds_read_b128 v[60:63], v8 offset:800
	s_waitcnt lgkmcnt(4)
	s_waitcnt vmcnt(28)
	v_fmac_f32_e32 v35, v64, v84
	v_fmac_f32_e32 v34, v68, v84
	v_fmac_f32_e32 v33, v72, v84
	v_fmac_f32_e32 v32, v76, v84
	v_fmac_f32_e32 v35, v65, v85
	v_fmac_f32_e32 v34, v69, v85
	v_fmac_f32_e32 v33, v73, v85
	v_fmac_f32_e32 v32, v77, v85
	v_fmac_f32_e32 v35, v66, v86
	v_fmac_f32_e32 v34, v70, v86
	v_fmac_f32_e32 v33, v74, v86
	v_fmac_f32_e32 v32, v78, v86
	v_fmac_f32_e32 v35, v67, v87
	v_fmac_f32_e32 v34, v71, v87
	v_fmac_f32_e32 v33, v75, v87
	v_fmac_f32_e32 v32, v79, v87
	global_load_dword v116, v[36:37], off nt
	v_lshl_add_u64 v[36:37], v[36:37], 0, s[92:93]
	global_load_dword v117, v[36:37], off nt
	v_lshl_add_u64 v[36:37], v[36:37], 0, s[92:93]
	global_load_dword v118, v[36:37], off nt
	v_lshl_add_u64 v[36:37], v[36:37], 0, s[92:93]
	global_load_dword v119, v[36:37], off nt
	v_lshl_add_u64 v[36:37], v[36:37], 0, s[92:93]
	ds_read_b128 v[64:67], v8 offset:48
	ds_read_b128 v[68:71], v8 offset:304
	ds_read_b128 v[72:75], v8 offset:560
	ds_read_b128 v[76:79], v8 offset:816
	s_waitcnt lgkmcnt(4)
	s_waitcnt vmcnt(28)
	v_fmac_f32_e32 v35, v48, v88
	v_fmac_f32_e32 v34, v52, v88
	v_fmac_f32_e32 v33, v56, v88
	v_fmac_f32_e32 v32, v60, v88
	v_fmac_f32_e32 v35, v49, v89
	v_fmac_f32_e32 v34, v53, v89
	v_fmac_f32_e32 v33, v57, v89
	v_fmac_f32_e32 v32, v61, v89
	v_fmac_f32_e32 v35, v50, v90
	v_fmac_f32_e32 v34, v54, v90
	v_fmac_f32_e32 v33, v58, v90
	v_fmac_f32_e32 v32, v62, v90
	v_fmac_f32_e32 v35, v51, v91
	v_fmac_f32_e32 v34, v55, v91
	v_fmac_f32_e32 v33, v59, v91
	v_fmac_f32_e32 v32, v63, v91
	global_load_dword v120, v[36:37], off nt
	v_lshl_add_u64 v[36:37], v[36:37], 0, s[92:93]
	global_load_dword v121, v[36:37], off nt
	v_lshl_add_u64 v[36:37], v[36:37], 0, s[92:93]
	global_load_dword v122, v[36:37], off nt
	v_lshl_add_u64 v[36:37], v[36:37], 0, s[92:93]
	global_load_dword v123, v[36:37], off nt
	v_lshl_add_u64 v[36:37], v[36:37], 0, s[92:93]
	ds_read_b128 v[48:51], v8 offset:64
	ds_read_b128 v[52:55], v8 offset:320
	ds_read_b128 v[56:59], v8 offset:576
	ds_read_b128 v[60:63], v8 offset:832
	s_waitcnt lgkmcnt(4)
	s_waitcnt vmcnt(28)
	v_fmac_f32_e32 v35, v64, v92
	v_fmac_f32_e32 v34, v68, v92
	v_fmac_f32_e32 v33, v72, v92
	v_fmac_f32_e32 v32, v76, v92
	v_fmac_f32_e32 v35, v65, v93
	v_fmac_f32_e32 v34, v69, v93
	v_fmac_f32_e32 v33, v73, v93
	v_fmac_f32_e32 v32, v77, v93
	v_fmac_f32_e32 v35, v66, v94
	v_fmac_f32_e32 v34, v70, v94
	v_fmac_f32_e32 v33, v74, v94
	v_fmac_f32_e32 v32, v78, v94
	v_fmac_f32_e32 v35, v67, v95
	v_fmac_f32_e32 v34, v71, v95
	v_fmac_f32_e32 v33, v75, v95
	v_fmac_f32_e32 v32, v79, v95
	global_load_dword v124, v[36:37], off nt
	v_lshl_add_u64 v[36:37], v[36:37], 0, s[92:93]
	global_load_dword v125, v[36:37], off nt
	v_lshl_add_u64 v[36:37], v[36:37], 0, s[92:93]
	global_load_dword v126, v[36:37], off nt
	v_lshl_add_u64 v[36:37], v[36:37], 0, s[92:93]
	global_load_dword v127, v[36:37], off nt
	v_lshl_add_u64 v[36:37], v[36:37], 0, s[92:93]
	ds_read_b128 v[64:67], v8 offset:80
	ds_read_b128 v[68:71], v8 offset:336
	ds_read_b128 v[72:75], v8 offset:592
	ds_read_b128 v[76:79], v8 offset:848
	s_waitcnt lgkmcnt(4)
	s_waitcnt vmcnt(28)
	v_fmac_f32_e32 v35, v48, v96
	v_fmac_f32_e32 v34, v52, v96
	v_fmac_f32_e32 v33, v56, v96
	v_fmac_f32_e32 v32, v60, v96
	v_fmac_f32_e32 v35, v49, v97
	v_fmac_f32_e32 v34, v53, v97
	v_fmac_f32_e32 v33, v57, v97
	v_fmac_f32_e32 v32, v61, v97
	v_fmac_f32_e32 v35, v50, v98
	v_fmac_f32_e32 v34, v54, v98
	v_fmac_f32_e32 v33, v58, v98
	v_fmac_f32_e32 v32, v62, v98
	v_fmac_f32_e32 v35, v51, v99
	v_fmac_f32_e32 v34, v55, v99
	v_fmac_f32_e32 v33, v59, v99
	v_fmac_f32_e32 v32, v63, v99
	global_load_dword v128, v[36:37], off nt
	v_lshl_add_u64 v[36:37], v[36:37], 0, s[92:93]
	global_load_dword v129, v[36:37], off nt
	v_lshl_add_u64 v[36:37], v[36:37], 0, s[92:93]
	global_load_dword v130, v[36:37], off nt
	v_lshl_add_u64 v[36:37], v[36:37], 0, s[92:93]
	global_load_dword v131, v[36:37], off nt
	v_lshl_add_u64 v[36:37], v[36:37], 0, s[92:93]
	ds_read_b128 v[48:51], v8 offset:96
	ds_read_b128 v[52:55], v8 offset:352
	ds_read_b128 v[56:59], v8 offset:608
	ds_read_b128 v[60:63], v8 offset:864
	s_waitcnt lgkmcnt(4)
	s_waitcnt vmcnt(28)
	v_fmac_f32_e32 v35, v64, v100
	v_fmac_f32_e32 v34, v68, v100
	v_fmac_f32_e32 v33, v72, v100
	v_fmac_f32_e32 v32, v76, v100
	v_fmac_f32_e32 v35, v65, v101
	v_fmac_f32_e32 v34, v69, v101
	v_fmac_f32_e32 v33, v73, v101
	v_fmac_f32_e32 v32, v77, v101
	v_fmac_f32_e32 v35, v66, v102
	v_fmac_f32_e32 v34, v70, v102
	v_fmac_f32_e32 v33, v74, v102
	v_fmac_f32_e32 v32, v78, v102
	v_fmac_f32_e32 v35, v67, v103
	v_fmac_f32_e32 v34, v71, v103
	v_fmac_f32_e32 v33, v75, v103
	v_fmac_f32_e32 v32, v79, v103
	global_load_dword v132, v[36:37], off nt
	v_lshl_add_u64 v[36:37], v[36:37], 0, s[92:93]
	global_load_dword v133, v[36:37], off nt
	v_lshl_add_u64 v[36:37], v[36:37], 0, s[92:93]
	global_load_dword v134, v[36:37], off nt
	v_lshl_add_u64 v[36:37], v[36:37], 0, s[92:93]
	global_load_dword v135, v[36:37], off nt
	v_lshl_add_u64 v[36:37], v[36:37], 0, s[92:93]
	ds_read_b128 v[64:67], v8 offset:112
	ds_read_b128 v[68:71], v8 offset:368
	ds_read_b128 v[72:75], v8 offset:624
	ds_read_b128 v[76:79], v8 offset:880
	s_waitcnt lgkmcnt(4)
	s_waitcnt vmcnt(28)
	v_fmac_f32_e32 v35, v48, v104
	v_fmac_f32_e32 v34, v52, v104
	v_fmac_f32_e32 v33, v56, v104
	v_fmac_f32_e32 v32, v60, v104
	v_fmac_f32_e32 v35, v49, v105
	v_fmac_f32_e32 v34, v53, v105
	v_fmac_f32_e32 v33, v57, v105
	v_fmac_f32_e32 v32, v61, v105
	v_fmac_f32_e32 v35, v50, v106
	v_fmac_f32_e32 v34, v54, v106
	v_fmac_f32_e32 v33, v58, v106
	v_fmac_f32_e32 v32, v62, v106
	v_fmac_f32_e32 v35, v51, v107
	v_fmac_f32_e32 v34, v55, v107
	v_fmac_f32_e32 v33, v59, v107
	v_fmac_f32_e32 v32, v63, v107
	global_load_dword v136, v[36:37], off nt
	v_lshl_add_u64 v[36:37], v[36:37], 0, s[92:93]
	global_load_dword v137, v[36:37], off nt
	v_lshl_add_u64 v[36:37], v[36:37], 0, s[92:93]
	global_load_dword v138, v[36:37], off nt
	v_lshl_add_u64 v[36:37], v[36:37], 0, s[92:93]
	global_load_dword v139, v[36:37], off nt
	v_lshl_add_u64 v[36:37], v[36:37], 0, s[92:93]
	ds_read_b128 v[48:51], v8 offset:128
	ds_read_b128 v[52:55], v8 offset:384
	ds_read_b128 v[56:59], v8 offset:640
	ds_read_b128 v[60:63], v8 offset:896
	s_waitcnt lgkmcnt(4)
	s_waitcnt vmcnt(28)
	v_fmac_f32_e32 v35, v64, v108
	v_fmac_f32_e32 v34, v68, v108
	v_fmac_f32_e32 v33, v72, v108
	v_fmac_f32_e32 v32, v76, v108
	v_fmac_f32_e32 v35, v65, v109
	v_fmac_f32_e32 v34, v69, v109
	v_fmac_f32_e32 v33, v73, v109
	v_fmac_f32_e32 v32, v77, v109
	v_fmac_f32_e32 v35, v66, v110
	v_fmac_f32_e32 v34, v70, v110
	v_fmac_f32_e32 v33, v74, v110
	v_fmac_f32_e32 v32, v78, v110
	v_fmac_f32_e32 v35, v67, v111
	v_fmac_f32_e32 v34, v71, v111
	v_fmac_f32_e32 v33, v75, v111
	v_fmac_f32_e32 v32, v79, v111
	global_load_dword v140, v[36:37], off nt
	v_lshl_add_u64 v[36:37], v[36:37], 0, s[92:93]
	global_load_dword v141, v[36:37], off nt
	v_lshl_add_u64 v[36:37], v[36:37], 0, s[92:93]
	global_load_dword v142, v[36:37], off nt
	v_lshl_add_u64 v[36:37], v[36:37], 0, s[92:93]
	global_load_dword v143, v[36:37], off nt
	ds_read_b128 v[64:67], v8 offset:144
	ds_read_b128 v[68:71], v8 offset:400
	ds_read_b128 v[72:75], v8 offset:656
	ds_read_b128 v[76:79], v8 offset:912
	s_waitcnt lgkmcnt(4)
	s_waitcnt vmcnt(28)
	v_fmac_f32_e32 v35, v48, v112
	v_fmac_f32_e32 v34, v52, v112
	v_fmac_f32_e32 v33, v56, v112
	v_fmac_f32_e32 v32, v60, v112
	v_fmac_f32_e32 v35, v49, v113
	v_fmac_f32_e32 v34, v53, v113
	v_fmac_f32_e32 v33, v57, v113
	v_fmac_f32_e32 v32, v61, v113
	v_fmac_f32_e32 v35, v50, v114
	v_fmac_f32_e32 v34, v54, v114
	v_fmac_f32_e32 v33, v58, v114
	v_fmac_f32_e32 v32, v62, v114
	v_fmac_f32_e32 v35, v51, v115
	v_fmac_f32_e32 v34, v55, v115
	v_fmac_f32_e32 v33, v59, v115
	v_fmac_f32_e32 v32, v63, v115
	ds_read_b128 v[48:51], v8 offset:160
	ds_read_b128 v[52:55], v8 offset:416
	ds_read_b128 v[56:59], v8 offset:672
	ds_read_b128 v[60:63], v8 offset:928
	s_waitcnt lgkmcnt(4)
	s_waitcnt vmcnt(24)
	v_fmac_f32_e32 v35, v64, v116
	v_fmac_f32_e32 v34, v68, v116
	v_fmac_f32_e32 v33, v72, v116
	v_fmac_f32_e32 v32, v76, v116
	v_fmac_f32_e32 v35, v65, v117
	v_fmac_f32_e32 v34, v69, v117
	v_fmac_f32_e32 v33, v73, v117
	v_fmac_f32_e32 v32, v77, v117
	v_fmac_f32_e32 v35, v66, v118
	v_fmac_f32_e32 v34, v70, v118
	v_fmac_f32_e32 v33, v74, v118
	v_fmac_f32_e32 v32, v78, v118
	v_fmac_f32_e32 v35, v67, v119
	v_fmac_f32_e32 v34, v71, v119
	v_fmac_f32_e32 v33, v75, v119
	v_fmac_f32_e32 v32, v79, v119
	ds_read_b128 v[64:67], v8 offset:176
	ds_read_b128 v[68:71], v8 offset:432
	ds_read_b128 v[72:75], v8 offset:688
	ds_read_b128 v[76:79], v8 offset:944
	s_waitcnt lgkmcnt(4)
	s_waitcnt vmcnt(20)
	v_fmac_f32_e32 v35, v48, v120
	v_fmac_f32_e32 v34, v52, v120
	v_fmac_f32_e32 v33, v56, v120
	v_fmac_f32_e32 v32, v60, v120
	v_fmac_f32_e32 v35, v49, v121
	v_fmac_f32_e32 v34, v53, v121
	v_fmac_f32_e32 v33, v57, v121
	v_fmac_f32_e32 v32, v61, v121
	v_fmac_f32_e32 v35, v50, v122
	v_fmac_f32_e32 v34, v54, v122
	v_fmac_f32_e32 v33, v58, v122
	v_fmac_f32_e32 v32, v62, v122
	v_fmac_f32_e32 v35, v51, v123
	v_fmac_f32_e32 v34, v55, v123
	v_fmac_f32_e32 v33, v59, v123
	v_fmac_f32_e32 v32, v63, v123
	ds_read_b128 v[48:51], v8 offset:192
	ds_read_b128 v[52:55], v8 offset:448
	ds_read_b128 v[56:59], v8 offset:704
	ds_read_b128 v[60:63], v8 offset:960
	s_waitcnt lgkmcnt(4)
	s_waitcnt vmcnt(16)
	v_fmac_f32_e32 v35, v64, v124
	v_fmac_f32_e32 v34, v68, v124
	v_fmac_f32_e32 v33, v72, v124
	v_fmac_f32_e32 v32, v76, v124
	v_fmac_f32_e32 v35, v65, v125
	v_fmac_f32_e32 v34, v69, v125
	v_fmac_f32_e32 v33, v73, v125
	v_fmac_f32_e32 v32, v77, v125
	v_fmac_f32_e32 v35, v66, v126
	v_fmac_f32_e32 v34, v70, v126
	v_fmac_f32_e32 v33, v74, v126
	v_fmac_f32_e32 v32, v78, v126
	v_fmac_f32_e32 v35, v67, v127
	v_fmac_f32_e32 v34, v71, v127
	v_fmac_f32_e32 v33, v75, v127
	v_fmac_f32_e32 v32, v79, v127
	ds_read_b128 v[64:67], v8 offset:208
	ds_read_b128 v[68:71], v8 offset:464
	ds_read_b128 v[72:75], v8 offset:720
	ds_read_b128 v[76:79], v8 offset:976
	s_waitcnt lgkmcnt(4)
	s_waitcnt vmcnt(12)
	v_fmac_f32_e32 v35, v48, v128
	v_fmac_f32_e32 v34, v52, v128
	v_fmac_f32_e32 v33, v56, v128
	v_fmac_f32_e32 v32, v60, v128
	v_fmac_f32_e32 v35, v49, v129
	v_fmac_f32_e32 v34, v53, v129
	v_fmac_f32_e32 v33, v57, v129
	v_fmac_f32_e32 v32, v61, v129
	v_fmac_f32_e32 v35, v50, v130
	v_fmac_f32_e32 v34, v54, v130
	v_fmac_f32_e32 v33, v58, v130
	v_fmac_f32_e32 v32, v62, v130
	v_fmac_f32_e32 v35, v51, v131
	v_fmac_f32_e32 v34, v55, v131
	v_fmac_f32_e32 v33, v59, v131
	v_fmac_f32_e32 v32, v63, v131
	ds_read_b128 v[48:51], v8 offset:224
	ds_read_b128 v[52:55], v8 offset:480
	ds_read_b128 v[56:59], v8 offset:736
	ds_read_b128 v[60:63], v8 offset:992
	s_waitcnt lgkmcnt(4)
	s_waitcnt vmcnt(8)
	v_fmac_f32_e32 v35, v64, v132
	v_fmac_f32_e32 v34, v68, v132
	v_fmac_f32_e32 v33, v72, v132
	v_fmac_f32_e32 v32, v76, v132
	v_fmac_f32_e32 v35, v65, v133
	v_fmac_f32_e32 v34, v69, v133
	v_fmac_f32_e32 v33, v73, v133
	v_fmac_f32_e32 v32, v77, v133
	v_fmac_f32_e32 v35, v66, v134
	v_fmac_f32_e32 v34, v70, v134
	v_fmac_f32_e32 v33, v74, v134
	v_fmac_f32_e32 v32, v78, v134
	v_fmac_f32_e32 v35, v67, v135
	v_fmac_f32_e32 v34, v71, v135
	v_fmac_f32_e32 v33, v75, v135
	v_fmac_f32_e32 v32, v79, v135
	ds_read_b128 v[64:67], v8 offset:240
	ds_read_b128 v[68:71], v8 offset:496
	ds_read_b128 v[72:75], v8 offset:752
	ds_read_b128 v[76:79], v8 offset:1008
	s_waitcnt lgkmcnt(4)
	s_waitcnt vmcnt(4)
	v_fmac_f32_e32 v35, v48, v136
	v_fmac_f32_e32 v34, v52, v136
	v_fmac_f32_e32 v33, v56, v136
	v_fmac_f32_e32 v32, v60, v136
	v_fmac_f32_e32 v35, v49, v137
	v_fmac_f32_e32 v34, v53, v137
	v_fmac_f32_e32 v33, v57, v137
	v_fmac_f32_e32 v32, v61, v137
	v_fmac_f32_e32 v35, v50, v138
	v_fmac_f32_e32 v34, v54, v138
	v_fmac_f32_e32 v33, v58, v138
	v_fmac_f32_e32 v32, v62, v138
	v_fmac_f32_e32 v35, v51, v139
	v_fmac_f32_e32 v34, v55, v139
	v_fmac_f32_e32 v33, v59, v139
	v_fmac_f32_e32 v32, v63, v139
	s_waitcnt lgkmcnt(0)
	s_waitcnt vmcnt(0)
	v_fmac_f32_e32 v35, v64, v140
	v_fmac_f32_e32 v34, v68, v140
	v_fmac_f32_e32 v33, v72, v140
	v_fmac_f32_e32 v32, v76, v140
	v_fmac_f32_e32 v35, v65, v141
	v_fmac_f32_e32 v34, v69, v141
	v_fmac_f32_e32 v33, v73, v141
	v_fmac_f32_e32 v32, v77, v141
	v_fmac_f32_e32 v35, v66, v142
	v_fmac_f32_e32 v34, v70, v142
	v_fmac_f32_e32 v33, v74, v142
	v_fmac_f32_e32 v32, v78, v142
	v_fmac_f32_e32 v35, v67, v143
	v_fmac_f32_e32 v34, v71, v143
	v_fmac_f32_e32 v33, v75, v143
	v_fmac_f32_e32 v32, v79, v143
	s_and_b32 s1, 0xffff, s1
	s_cmp_eq_u32 s0, 0
	s_cbranch_scc0 .LBB0_340
	s_mul_i32 s4, s1, 0xc00
	v_add_u32_e32 v2, s4, v28
	v_ashrrev_i32_e32 v3, 31, v2
	v_lshl_add_u64 v[2:3], v[2:3], 2, s[42:43]
	global_load_dword v0, v[2:3], off
	s_waitcnt vmcnt(0)
	v_pk_add_f32 v[34:35], v[34:35], v[0:1] op_sel_hi:[1,0]
	v_pk_add_f32 v[32:33], v[32:33], v[0:1] op_sel_hi:[1,0]
